# nt hint on the final phase residual-row loads
# speedup vs baseline: 1.0205x; 1.0018x over previous
.LBB0_19:
	s_load_dwordx2 s[6:7], s[0:1], 0x98
	s_waitcnt lgkmcnt(0)
	s_add_u32 s6, s6, s26
	s_addc_u32 s7, s7, s27
	global_load_dwordx4 v[0:3], v97, s[6:7] offset:-48
	s_load_dwordx2 s[6:7], s[0:1], 0x98
	s_waitcnt lgkmcnt(0)
	v_lshl_add_u64 v[4:5], s[6:7], 0, v[10:11]
	global_load_dwordx2 v[16:17], v[4:5], off offset:-1536 nt
	s_load_dwordx2 s[6:7], s[0:1], 0x98
	s_waitcnt lgkmcnt(0)
	v_lshl_add_u64 v[4:5], s[6:7], 0, v[10:11]
	global_load_dwordx2 v[14:15], v[4:5], off offset:-1024 nt
	s_load_dwordx2 s[6:7], s[0:1], 0x98
	s_waitcnt lgkmcnt(0)
	v_lshl_add_u64 v[4:5], s[6:7], 0, v[10:11]
	global_load_dwordx2 v[12:13], v[4:5], off offset:-512 nt
	s_load_dwordx2 s[6:7], s[0:1], 0x98
	s_waitcnt lgkmcnt(0)
	v_lshl_add_u64 v[4:5], s[6:7], 0, v[10:11]
	global_load_dwordx2 v[26:27], v[4:5], off nt
	s_load_dwordx2 s[6:7], s[0:1], 0x98
	v_subrev_co_u32_e32 v10, vcc, s18, v10
	s_waitcnt lgkmcnt(0)
	s_add_u32 s6, s6, s26
	s_addc_u32 s7, s7, s27
	global_load_dwordx4 v[22:25], v97, s[6:7] offset:-32
	s_load_dwordx2 s[6:7], s[0:1], 0x98
	s_add_i32 s22, s12, -2
	s_ashr_i32 s23, s22, 31
	s_lshl_b64 s[8:9], s[22:23], 11
	v_subb_co_u32_e32 v11, vcc, v11, v52, vcc
	s_waitcnt lgkmcnt(0)
	s_add_u32 s6, s6, s8
	s_addc_u32 s7, s7, s9
	v_lshl_add_u64 v[4:5], s[6:7], 0, v[96:97]
	v_add_co_u32_e32 v4, vcc, s51, v4
	s_waitcnt vmcnt(5)
	v_mov_b32_e32 v30, v1
	v_addc_co_u32_e32 v5, vcc, 0, v5, vcc
	global_load_dwordx2 v[28:29], v[4:5], off nt
	s_load_dwordx2 s[6:7], s[0:1], 0x98
	v_mov_b32_e32 v31, v2
	v_mov_b32_e32 v1, v3
	v_pk_add_f32 v[0:1], v[30:31], v[0:1]
	s_waitcnt vmcnt(5)
	v_lshlrev_b32_e32 v32, 16, v16
	s_waitcnt lgkmcnt(0)
	s_add_u32 s6, s6, s8
	s_addc_u32 s7, s7, s9
	v_lshl_add_u64 v[4:5], s[6:7], 0, v[96:97]
	v_add_co_u32_e32 v4, vcc, s51, v4
	v_and_b32_e32 v33, 0xffff0000, v16
	s_nop 0
	v_addc_co_u32_e32 v5, vcc, 0, v5, vcc
	global_load_dwordx2 v[44:45], v[4:5], off offset:512 nt
	s_load_dwordx2 s[6:7], s[0:1], 0x98
	v_lshlrev_b32_e32 v36, 16, v17
	v_and_b32_e32 v37, 0xffff0000, v17
	s_waitcnt vmcnt(5)
	v_lshlrev_b32_e32 v40, 16, v14
	v_and_b32_e32 v41, 0xffff0000, v14
	s_waitcnt lgkmcnt(0)
	s_add_u32 s6, s6, s8
	s_addc_u32 s7, s7, s9
	v_lshl_add_u64 v[4:5], s[6:7], 0, v[96:97]
	v_add_co_u32_e32 v4, vcc, s51, v4
	s_waitcnt vmcnt(4)
	v_lshlrev_b32_e32 v42, 16, v12
	v_addc_co_u32_e32 v5, vcc, 0, v5, vcc
	global_load_dwordx2 v[20:21], v[4:5], off offset:1024 nt
	s_load_dwordx2 s[6:7], s[0:1], 0x98
	v_and_b32_e32 v43, 0xffff0000, v12
	v_lshlrev_b32_e32 v46, 16, v13
	v_and_b32_e32 v47, 0xffff0000, v13
	s_waitcnt vmcnt(4)
	v_lshlrev_b32_e32 v48, 16, v26
	s_waitcnt lgkmcnt(0)
	s_add_u32 s6, s6, s8
	s_addc_u32 s7, s7, s9
	v_lshl_add_u64 v[4:5], s[6:7], 0, v[96:97]
	v_add_co_u32_e32 v4, vcc, s51, v4
	v_and_b32_e32 v49, 0xffff0000, v26
	s_nop 0
	v_addc_co_u32_e32 v5, vcc, 0, v5, vcc
	global_load_dwordx2 v[18:19], v[4:5], off offset:1536 nt
	s_load_dwordx2 s[6:7], s[0:1], 0x98
	v_lshlrev_b32_e32 v54, 16, v27
	v_and_b32_e32 v55, 0xffff0000, v27
	s_waitcnt vmcnt(4)
	v_mov_b32_e32 v26, v23
	v_mov_b32_e32 v27, v24
	s_waitcnt lgkmcnt(0)
	s_add_u32 s6, s6, s26
	s_addc_u32 s7, s7, s27
	global_load_dwordx4 v[4:7], v97, s[6:7] offset:-16
	s_load_dwordx2 s[8:9], s[0:1], 0x98
	s_add_i32 s20, s12, -1
	s_ashr_i32 s21, s20, 31
	s_lshl_b64 s[6:7], s[20:21], 11
	v_mov_b32_e32 v23, v25
	s_waitcnt lgkmcnt(0)
	s_add_u32 s8, s8, s6
	s_addc_u32 s9, s9, s7
	v_lshl_add_u64 v[30:31], s[8:9], 0, v[96:97]
	v_add_co_u32_e32 v30, vcc, s51, v30
	v_pk_add_f32 v[22:23], v[26:27], v[22:23]
	s_nop 0
	v_addc_co_u32_e32 v31, vcc, 0, v31, vcc
	global_load_dwordx2 v[16:17], v[30:31], off nt
	s_load_dwordx2 s[8:9], s[0:1], 0x98
	v_lshlrev_b32_e32 v30, 16, v15
	v_and_b32_e32 v31, 0xffff0000, v15
	v_mov_b32_e32 v3, v0
	v_mov_b32_e32 v2, v22
	s_waitcnt lgkmcnt(0)
	s_add_u32 s8, s8, s6
	s_addc_u32 s9, s9, s7
	v_lshl_add_u64 v[14:15], s[8:9], 0, v[96:97]
	v_add_co_u32_e32 v14, vcc, s51, v14
	v_mov_b32_e32 v0, v23
	s_nop 0
	v_addc_co_u32_e32 v15, vcc, 0, v15, vcc
	global_load_dwordx2 v[14:15], v[14:15], off offset:512 nt
	s_load_dwordx2 s[8:9], s[0:1], 0x98
	v_pk_add_f32 v[0:1], v[2:3], v[0:1]
	s_waitcnt lgkmcnt(0)
	s_add_u32 s8, s8, s6
	s_addc_u32 s9, s9, s7
	v_lshl_add_u64 v[12:13], s[8:9], 0, v[96:97]
	v_add_co_u32_e32 v12, vcc, s51, v12
	v_pk_fma_f32 v[0:1], v[0:1], s[30:31], v[172:173] op_sel_hi:[1,0,0]
	s_nop 0
	v_addc_co_u32_e32 v13, vcc, 0, v13, vcc
	global_load_dwordx2 v[12:13], v[12:13], off offset:1024 nt
	s_load_dwordx2 s[8:9], s[0:1], 0x98
	v_mul_f32_e32 v22, 0x4b800000, v1
	v_mul_f32_e32 v23, 0x4b800000, v0
	s_waitcnt lgkmcnt(0)
	s_add_u32 s6, s8, s6
	s_addc_u32 s7, s9, s7
	v_lshl_add_u64 v[2:3], s[6:7], 0, v[96:97]
	v_add_co_u32_e32 v2, vcc, s51, v2
	v_cmp_gt_f32_e64 s[6:7], s59, v0
	v_cmp_gt_f32_e64 s[8:9], s59, v1
	v_addc_co_u32_e32 v3, vcc, 0, v3, vcc
	s_nop 0
	v_cndmask_b32_e64 v1, v1, v22, s[8:9]
	v_cndmask_b32_e64 v0, v0, v23, s[6:7]
	global_load_dwordx2 v[34:35], v[2:3], off offset:1536 nt
	s_load_dwordx2 s[28:29], s[0:1], 0x98
	v_rsq_f32_e32 v22, v1
	v_rsq_f32_e32 v23, v0
	s_waitcnt vmcnt(8)
	v_lshlrev_b32_e32 v0, 16, v28
	v_and_b32_e32 v1, 0xffff0000, v28
	v_mul_f32_e32 v24, 0x45800000, v22
	v_mul_f32_e32 v25, 0x45800000, v23
	s_waitcnt lgkmcnt(0)
	s_add_u32 s28, s28, s26
	v_lshlrev_b32_e32 v2, 16, v29
	v_and_b32_e32 v3, 0xffff0000, v29
	v_cndmask_b32_e64 v24, v22, v24, s[8:9]
	v_cndmask_b32_e64 v56, v23, v25, s[6:7]
	s_addc_u32 s29, s29, s27
	v_pk_mul_f32 v[38:39], v[24:25], v[32:33] op_sel_hi:[0,1]
	v_pk_mul_f32 v[32:33], v[24:25], v[40:41] op_sel_hi:[0,1]
	v_pk_mul_f32 v[28:29], v[24:25], v[42:43] op_sel_hi:[0,1]
	v_pk_mul_f32 v[40:41], v[56:57], v[2:3] op_sel_hi:[0,1]
	v_pk_mul_f32 v[42:43], v[56:57], v[0:1] op_sel_hi:[0,1]
	global_load_dwordx4 v[0:3], v97, s[28:29]
	s_load_dwordx2 s[8:9], s[0:1], 0x98
	s_ashr_i32 s13, s12, 31
	s_lshl_b64 s[6:7], s[12:13], 11
	v_pk_mul_f32 v[36:37], v[24:25], v[36:37] op_sel_hi:[0,1]
	v_pk_mul_f32 v[30:31], v[24:25], v[30:31] op_sel_hi:[0,1]
	s_waitcnt lgkmcnt(0)
	s_add_u32 s8, s8, s6
	s_addc_u32 s9, s9, s7
	v_pk_mul_f32 v[26:27], v[24:25], v[46:47] op_sel_hi:[0,1]
	v_pk_mul_f32 v[22:23], v[24:25], v[54:55] op_sel_hi:[0,1]
	v_pk_mul_f32 v[24:25], v[24:25], v[48:49] op_sel_hi:[0,1]
	v_lshl_add_u64 v[48:49], s[8:9], 0, v[96:97]
	v_add_co_u32_e32 v48, vcc, s51, v48
	s_waitcnt vmcnt(8)
	v_lshlrev_b32_e32 v46, 16, v44
	v_addc_co_u32_e32 v49, vcc, 0, v49, vcc
	global_load_dwordx2 v[62:63], v[48:49], off nt
	s_load_dwordx2 s[8:9], s[0:1], 0x98
	s_waitcnt vmcnt(5)
	v_lshlrev_b32_e32 v78, 16, v16
	v_and_b32_e32 v79, 0xffff0000, v16
	v_lshlrev_b32_e32 v80, 16, v17
	v_and_b32_e32 v81, 0xffff0000, v17
	s_waitcnt lgkmcnt(0)
	s_add_u32 s8, s8, s6
	s_addc_u32 s9, s9, s7
	v_lshl_add_u64 v[54:55], s[8:9], 0, v[96:97]
	v_add_co_u32_e32 v54, vcc, s51, v54
	v_and_b32_e32 v47, 0xffff0000, v44
	s_nop 0
	v_addc_co_u32_e32 v55, vcc, 0, v55, vcc
	global_load_dwordx2 v[64:65], v[54:55], off offset:512 nt
	s_load_dwordx2 s[8:9], s[0:1], 0x98
	v_lshlrev_b32_e32 v54, 16, v18
	v_and_b32_e32 v55, 0xffff0000, v18
	v_lshlrev_b32_e32 v18, 16, v19
	v_and_b32_e32 v19, 0xffff0000, v19
	s_waitcnt lgkmcnt(0)
	s_add_u32 s8, s8, s6
	s_addc_u32 s9, s9, s7
	v_lshl_add_u64 v[58:59], s[8:9], 0, v[96:97]
	v_pk_mul_f32 v[66:67], v[56:57], v[18:19] op_sel_hi:[0,1]
	v_add_co_u32_e32 v18, vcc, s51, v58
	v_lshlrev_b32_e32 v44, 16, v45
	s_nop 0
	v_addc_co_u32_e32 v19, vcc, 0, v59, vcc
	global_load_dwordx2 v[70:71], v[18:19], off offset:1024 nt
	s_load_dwordx2 s[8:9], s[0:1], 0x98
	v_mov_b32_e32 v18, v5
	v_mov_b32_e32 v19, v6
	v_mov_b32_e32 v5, v7
	v_pk_add_f32 v[72:73], v[18:19], v[4:5]
	s_waitcnt lgkmcnt(0)
	s_add_u32 s6, s8, s6
	s_addc_u32 s7, s9, s7
	v_lshl_add_u64 v[4:5], s[6:7], 0, v[96:97]
	v_add_co_u32_e32 v4, vcc, s51, v4
	v_and_b32_e32 v45, 0xffff0000, v45
	s_nop 0
	v_addc_co_u32_e32 v5, vcc, 0, v5, vcc
	global_load_dwordx2 v[76:77], v[4:5], off offset:1536 nt
	s_load_dwordx2 s[6:7], s[0:1], 0x88
	v_lshlrev_b32_e32 v48, 16, v20
	v_and_b32_e32 v49, 0xffff0000, v20
	v_lshlrev_b32_e32 v20, 16, v21
	v_and_b32_e32 v21, 0xffff0000, v21
	s_waitcnt lgkmcnt(0)
	global_load_dwordx4 v[4:7], v50, s[6:7]
	s_load_dwordx2 s[6:7], s[0:1], 0x88
	v_pk_mul_f32 v[44:45], v[56:57], v[44:45] op_sel_hi:[0,1]
	v_pk_mul_f32 v[46:47], v[56:57], v[46:47] op_sel_hi:[0,1]
	v_pk_mul_f32 v[20:21], v[56:57], v[20:21] op_sel_hi:[0,1]
	v_pk_mul_f32 v[48:49], v[56:57], v[48:49] op_sel_hi:[0,1]
	s_waitcnt lgkmcnt(0)
	global_load_dwordx4 v[16:19], v50, s[6:7] offset:1024
	s_load_dwordx2 s[6:7], s[0:1], 0x88
	v_pk_mul_f32 v[68:69], v[56:57], v[54:55] op_sel_hi:[0,1]
	v_mov_b32_e32 v75, v72
	s_waitcnt vmcnt(9)
	v_lshlrev_b32_e32 v82, 16, v14
	v_and_b32_e32 v83, 0xffff0000, v14
	s_waitcnt lgkmcnt(0)
	global_load_dwordx4 v[54:57], v50, s[6:7] offset:2048
	s_load_dwordx2 s[6:7], s[0:1], 0x88
	s_waitcnt vmcnt(7)
	v_mov_b32_e32 v90, v1
	v_mov_b32_e32 v91, v2
	v_mov_b32_e32 v1, v3
	v_pk_add_f32 v[0:1], v[90:91], v[0:1]
	s_waitcnt lgkmcnt(0)
	global_load_dwordx4 v[58:61], v50, s[6:7] offset:3072
	s_load_dwordx2 s[6:7], s[0:1], 0x90
	v_mov_b32_e32 v74, v0
	v_mov_b32_e32 v72, v1
	v_pk_add_f32 v[0:1], v[74:75], v[72:73]
	v_lshlrev_b32_e32 v14, 16, v15
	v_pk_fma_f32 v[0:1], v[0:1], s[30:31], v[172:173] op_sel_hi:[1,0,0]
	s_waitcnt lgkmcnt(0)
	v_lshl_add_u64 v[86:87], s[6:7], 0, v[8:9]
	v_mul_f32_e32 v2, 0x4b800000, v1
	v_mul_f32_e32 v3, 0x4b800000, v0
	v_cmp_gt_f32_e32 vcc, s59, v0
	v_cmp_gt_f32_e64 s[6:7], s59, v1
	v_and_b32_e32 v15, 0xffff0000, v15
	v_cndmask_b32_e32 v0, v0, v3, vcc
	v_cndmask_b32_e64 v1, v1, v2, s[6:7]
	v_rsq_f32_e32 v53, v1
	v_rsq_f32_e32 v72, v0
	s_waitcnt vmcnt(7)
	v_lshlrev_b32_e32 v0, 16, v62
	v_and_b32_e32 v1, 0xffff0000, v62
	v_lshlrev_b32_e32 v2, 16, v63
	v_and_b32_e32 v3, 0xffff0000, v63
	v_mul_f32_e32 v62, 0x45800000, v53
	v_mul_f32_e32 v63, 0x45800000, v72
	v_lshlrev_b32_e32 v84, 16, v12
	v_and_b32_e32 v85, 0xffff0000, v12
	v_lshlrev_b32_e32 v12, 16, v13
	v_and_b32_e32 v13, 0xffff0000, v13
	v_lshlrev_b32_e32 v88, 16, v34
	v_and_b32_e32 v89, 0xffff0000, v34
	v_lshlrev_b32_e32 v34, 16, v35
	v_and_b32_e32 v35, 0xffff0000, v35
	v_cndmask_b32_e64 v62, v53, v62, s[6:7]
	v_cndmask_b32_e32 v72, v72, v63, vcc
	v_pk_mul_f32 v[74:75], v[62:63], v[80:81] op_sel_hi:[0,1]
	v_pk_mul_f32 v[78:79], v[62:63], v[78:79] op_sel_hi:[0,1]
	v_pk_mul_f32 v[80:81], v[62:63], v[14:15] op_sel_hi:[0,1]
	v_pk_mul_f32 v[82:83], v[62:63], v[82:83] op_sel_hi:[0,1]
	v_pk_mul_f32 v[90:91], v[62:63], v[12:13] op_sel_hi:[0,1]
	v_pk_mul_f32 v[84:85], v[62:63], v[84:85] op_sel_hi:[0,1]
	v_pk_mul_f32 v[92:93], v[62:63], v[34:35] op_sel_hi:[0,1]
	v_pk_mul_f32 v[62:63], v[62:63], v[88:89] op_sel_hi:[0,1]
	v_pk_mul_f32 v[88:89], v[72:73], v[2:3] op_sel_hi:[0,1]
	v_pk_mul_f32 v[94:95], v[72:73], v[0:1] op_sel_hi:[0,1]
	s_waitcnt vmcnt(6)
	v_lshlrev_b32_e32 v0, 16, v64
	v_and_b32_e32 v1, 0xffff0000, v64
	v_lshlrev_b32_e32 v2, 16, v65
	v_and_b32_e32 v3, 0xffff0000, v65
	v_pk_mul_f32 v[64:65], v[72:73], v[2:3] op_sel_hi:[0,1]
	v_pk_mul_f32 v[98:99], v[72:73], v[0:1] op_sel_hi:[0,1]
	s_waitcnt vmcnt(5)
	v_lshlrev_b32_e32 v0, 16, v70
	v_and_b32_e32 v1, 0xffff0000, v70
	v_lshlrev_b32_e32 v2, 16, v71
	v_and_b32_e32 v3, 0xffff0000, v71
	v_pk_mul_f32 v[70:71], v[72:73], v[2:3] op_sel_hi:[0,1]
	v_pk_mul_f32 v[100:101], v[72:73], v[0:1] op_sel_hi:[0,1]
	s_lshl_b64 s[8:9], s[22:23], 12
	s_waitcnt vmcnt(4)
	v_lshlrev_b32_e32 v0, 16, v76
	v_and_b32_e32 v1, 0xffff0000, v76
	v_lshlrev_b32_e32 v2, 16, v77
	v_and_b32_e32 v3, 0xffff0000, v77
	v_pk_mul_f32 v[76:77], v[72:73], v[2:3] op_sel_hi:[0,1]
	v_pk_mul_f32 v[72:73], v[72:73], v[0:1] op_sel_hi:[0,1]
	s_waitcnt vmcnt(3)
	v_pk_mul_f32 v[0:1], v[4:5], v[38:39]
	v_pk_mul_f32 v[2:3], v[6:7], v[36:37]
	global_store_dwordx4 v[86:87], v[0:3], off offset:-3072 nt
	s_load_dwordx2 s[6:7], s[0:1], 0x90
	v_pk_mul_f32 v[12:13], v[4:5], v[42:43]
	v_pk_mul_f32 v[14:15], v[6:7], v[40:41]
	s_waitcnt vmcnt(3)
	v_pk_mul_f32 v[0:1], v[16:17], v[32:33]
	v_pk_mul_f32 v[2:3], v[18:19], v[30:31]
	s_waitcnt lgkmcnt(0)
	v_lshl_add_u64 v[30:31], s[6:7], 0, v[8:9]
	global_store_dwordx4 v[30:31], v[0:3], off offset:-2048 nt
	s_load_dwordx2 s[6:7], s[0:1], 0x90
	v_pk_mul_f32 v[34:35], v[4:5], v[78:79]
	s_waitcnt vmcnt(3)
	v_pk_mul_f32 v[0:1], v[54:55], v[28:29]
	v_pk_mul_f32 v[2:3], v[56:57], v[26:27]
	v_pk_mul_f32 v[36:37], v[6:7], v[74:75]
	s_waitcnt lgkmcnt(0)
	v_lshl_add_u64 v[26:27], s[6:7], 0, v[8:9]
	global_store_dwordx4 v[26:27], v[0:3], off offset:-1024 nt
	s_load_dwordx2 s[6:7], s[0:1], 0x90
	v_pk_mul_f32 v[4:5], v[4:5], v[94:95]
	s_waitcnt vmcnt(3)
	v_pk_mul_f32 v[0:1], v[58:59], v[24:25]
	v_pk_mul_f32 v[2:3], v[60:61], v[22:23]
	v_pk_mul_f32 v[6:7], v[6:7], v[88:89]
	s_waitcnt lgkmcnt(0)
	v_lshl_add_u64 v[22:23], s[6:7], 0, v[8:9]
	global_store_dwordx4 v[22:23], v[0:3], off nt
	s_load_dwordx2 s[6:7], s[0:1], 0x90
	v_subrev_co_u32_e32 v8, vcc, s16, v8
	v_pk_mul_f32 v[0:1], v[16:17], v[46:47]
	v_pk_mul_f32 v[2:3], v[18:19], v[44:45]
	s_waitcnt lgkmcnt(0)
	s_add_u32 s6, s6, s8
	s_addc_u32 s7, s7, s9
	global_store_dwordx4 v50, v[12:15], s[6:7] nt
	s_load_dwordx2 s[6:7], s[0:1], 0x90
	v_subb_co_u32_e32 v9, vcc, v9, v51, vcc
	v_pk_mul_f32 v[12:13], v[16:17], v[82:83]
	v_pk_mul_f32 v[14:15], v[18:19], v[80:81]
	s_waitcnt lgkmcnt(0)
	s_add_u32 s6, s6, s8
	s_addc_u32 s7, s7, s9
	global_store_dwordx4 v50, v[0:3], s[6:7] offset:1024 nt
	s_load_dwordx2 s[6:7], s[0:1], 0x90
	s_waitcnt lgkmcnt(0)
	s_add_u32 s6, s6, s8
	v_pk_mul_f32 v[0:1], v[54:55], v[48:49]
	v_pk_mul_f32 v[2:3], v[56:57], v[20:21]
	s_addc_u32 s7, s7, s9
	global_store_dwordx4 v50, v[0:3], s[6:7] offset:2048 nt
	s_load_dwordx2 s[6:7], s[0:1], 0x90
	s_waitcnt lgkmcnt(0)
	s_add_u32 s6, s6, s8
	v_pk_mul_f32 v[0:1], v[58:59], v[68:69]
	v_pk_mul_f32 v[2:3], v[60:61], v[66:67]
	s_addc_u32 s7, s7, s9
	global_store_dwordx4 v50, v[0:3], s[6:7] offset:3072 nt
	s_load_dwordx2 s[6:7], s[0:1], 0x90
	s_lshl_b64 s[8:9], s[20:21], 12
	v_pk_mul_f32 v[0:1], v[16:17], v[98:99]
	v_pk_mul_f32 v[2:3], v[18:19], v[64:65]
	v_pk_mul_f32 v[16:17], v[54:55], v[84:85]
	s_waitcnt lgkmcnt(0)
	s_add_u32 s6, s6, s8
	s_addc_u32 s7, s7, s9
	global_store_dwordx4 v50, v[34:37], s[6:7] nt
	s_load_dwordx2 s[6:7], s[0:1], 0x90
	v_pk_mul_f32 v[18:19], v[56:57], v[90:91]
	s_waitcnt lgkmcnt(0)
	s_add_u32 s6, s6, s8
	s_addc_u32 s7, s7, s9
	global_store_dwordx4 v50, v[12:15], s[6:7] offset:1024 nt
	s_load_dwordx2 s[6:7], s[0:1], 0x90
	s_waitcnt lgkmcnt(0)
	s_add_u32 s6, s6, s8
	s_addc_u32 s7, s7, s9
	global_store_dwordx4 v50, v[16:19], s[6:7] offset:2048 nt
	s_load_dwordx2 s[6:7], s[0:1], 0x90
	v_pk_mul_f32 v[14:15], v[58:59], v[62:63]
	v_pk_mul_f32 v[16:17], v[60:61], v[92:93]
	v_pk_mul_f32 v[12:13], v[54:55], v[100:101]
	s_waitcnt lgkmcnt(0)
	s_add_u32 s6, s6, s8
	s_addc_u32 s7, s7, s9
	global_store_dwordx4 v50, v[14:17], s[6:7] offset:3072 nt
	s_load_dwordx2 s[6:7], s[0:1], 0x90
	s_lshl_b64 s[8:9], s[12:13], 12
	v_pk_mul_f32 v[14:15], v[56:57], v[70:71]
	s_waitcnt lgkmcnt(0)
	s_add_u32 s6, s6, s8
	s_addc_u32 s7, s7, s9
	global_store_dwordx4 v50, v[4:7], s[6:7] nt
	s_load_dwordx2 s[6:7], s[0:1], 0x90
	s_waitcnt lgkmcnt(0)
	s_add_u32 s6, s6, s8
	s_addc_u32 s7, s7, s9
	global_store_dwordx4 v50, v[0:3], s[6:7] offset:1024 nt
	s_load_dwordx2 s[6:7], s[0:1], 0x90
	v_pk_mul_f32 v[4:5], v[58:59], v[72:73]
	v_pk_mul_f32 v[6:7], v[60:61], v[76:77]
	s_waitcnt lgkmcnt(0)
	s_add_u32 s6, s6, s8
	s_addc_u32 s7, s7, s9
	global_store_dwordx4 v50, v[12:15], s[6:7] offset:2048 nt
	s_load_dwordx2 s[6:7], s[0:1], 0x90
	s_waitcnt lgkmcnt(0)
	s_add_u32 s6, s6, s8
	s_addc_u32 s7, s7, s9
	s_add_i32 s4, s4, s10
	s_sub_i32 s12, s12, s10
	s_sub_u32 s26, s26, s14
	s_subb_u32 s27, s27, s15
	s_cmp_gt_i32 s4, 0x101ff
	global_store_dwordx4 v50, v[4:7], s[6:7] offset:3072 nt
	s_cbranch_scc0 .LBB0_19
